# grid sync: barrier-pointer s_load and expected-count load issued under the L2 write-back instead of after it (one wait covers both)
# speedup vs baseline: 1.0089x; 1.0089x over previous
; __global__ void __launch_bounds__(512) hybrid_layer_megakernel(Params p, int ph_lo, int ph_hi) {
;     ...
;     if (ph < ph_hi) { cg::this_grid().sync(); }
.LBB0_2201:
	s_load_dwordx2 s[4:5], s[84:85], 0x58
	buffer_wbl2 sc1
	s_mov_b64 s[6:7], exec
	v_mbcnt_lo_u32_b32 v1, s6, 0
	v_mbcnt_hi_u32_b32 v1, s7, v1
	v_cmp_eq_u32_e32 vcc, 0, v1
	s_waitcnt lgkmcnt(0)
	global_load_dword v0, v177, s[4:5] offset:40
	s_waitcnt vmcnt(0)
	s_and_saveexec_b64 s[8:9], vcc
	s_cbranch_execz .LBB0_2203
	s_bcnt1_i32_b64 s6, s[6:7]
	v_mov_b32_e32 v2, s6
	global_atomic_add v2, v177, v2, s[4:5] offset:32 sc0
